# grid barriers: non-leader workgroups issue the acquire L1 invalidate at the start of the wait instead of after the release flag
# speedup vs baseline: 1.0149x; 1.0131x over previous
; DI unsigned xb_ld(unsigned* p)              { return __hip_atomic_load(p, __ATOMIC_RELAXED, __HIP_MEMORY_SCOPE_AGENT); }
; DI unsigned xb_add(unsigned* p, unsigned v) { return __hip_atomic_fetch_add(p, v, __ATOMIC_RELAXED, __HIP_MEMORY_SCOPE_AGENT); }
; #define XB_SPIN(cond, bar) do { unsigned _sp = 0; while (cond) { __builtin_amdgcn_s_sleep(1); \
;     if ((++_sp & 255u) == 0u) { if (xb_ld(&(bar)[XB_TMO])) break; if (_sp > XB_SPIN_CAP) { atomicAdd(&(bar)[XB_TMO], 1u); break; } } } } while (0)
; DI void xcd_barrier(unsigned* bar, volatile __attribute__((address_space(3))) unsigned* st) {
;     ...
;         const unsigned old = xb_add(&bar[XB_XSUB(x)], 1u);
;         const unsigned gen = old / nloc;
;         if (old + 1u == (gen + 1u) * nloc) {
;             __builtin_amdgcn_fence(__ATOMIC_RELEASE, "agent");
;             asm volatile("s_waitcnt vmcnt(0)" ::: "memory");
;             const unsigned og = xb_add(&bar[XB_TOP], 1u);
;             const unsigned tg = og / nx;
;             if (og + 1u == (tg + 1u) * nx) xb_add(&bar[XB_TOPGEN], 1u);
;             else XB_SPIN(xb_ld(&bar[XB_TOPGEN]) == tg, bar);
;             __builtin_amdgcn_fence(__ATOMIC_ACQUIRE, "agent");
;             xb_add(&bar[XB_XGEN(x)], 1u);
;             asm volatile("s_waitcnt vmcnt(0)" ::: "memory");
;         } else {
;             XB_SPIN(xb_ld(&bar[XB_XGEN(x)]) == gen, bar);
;             __builtin_amdgcn_fence(__ATOMIC_ACQUIRE, "agent");
.LBB0_150:
	s_or_b64 exec, exec, s[8:9]
	v_cvt_f32_u32_e32 v4, v2
	s_waitcnt vmcnt(0)
	v_readfirstlane_b32 s3, v3
	v_sub_u32_e32 v3, 0, v2
	v_rcp_iflag_f32_e32 v4, v4
	v_add_u32_e32 v5, s3, v0
	v_mul_f32_e32 v4, 0x4f7ffffe, v4
	v_cvt_u32_f32_e32 v4, v4
	v_mul_lo_u32 v0, v3, v4
	v_mul_hi_u32 v0, v4, v0
	v_add_u32_e32 v0, v4, v0
	v_mul_hi_u32 v0, v5, v0
	v_mul_lo_u32 v3, v0, v2
	v_sub_u32_e32 v3, v5, v3
	v_add_u32_e32 v4, 1, v0
	v_cmp_ge_u32_e32 vcc, v3, v2
	s_nop 1
	v_cndmask_b32_e32 v0, v0, v4, vcc
	v_sub_u32_e32 v4, v3, v2
	v_cndmask_b32_e32 v3, v3, v4, vcc
	v_add_u32_e32 v4, 1, v0
	v_cmp_ge_u32_e32 vcc, v3, v2
	v_add_u32_e32 v3, 1, v5
	s_nop 0
	v_cndmask_b32_e32 v0, v0, v4, vcc
	v_mul_lo_u32 v4, v2, v0
	v_add_u32_e32 v2, v4, v2
	v_cmp_ne_u32_e32 vcc, v3, v2
	s_and_saveexec_b64 s[6:7], vcc
	s_xor_b64 s[6:7], exec, s[6:7]
	s_cbranch_execz .LBB0_164
	buffer_inv sc1
	s_waitcnt lgkmcnt(0)
	v_mov_b32_e32 v1, 0x2000
	global_load_dword v1, v1, s[4:5] offset:1024 sc1
	s_add_u32 s12, s4, 0x2400
	s_addc_u32 s13, s5, 0
	s_waitcnt vmcnt(0)
	v_cmp_eq_u32_e32 vcc, v1, v0
	s_and_saveexec_b64 s[8:9], vcc
	s_cbranch_execz .LBB0_163
	s_add_u32 s10, s70, 0x34e2300
	s_addc_u32 s11, s71, 0
	s_mov_b32 s3, 1
	s_mov_b64 s[14:15], 0
	v_mov_b32_e32 v1, 0
	s_branch .LBB0_154

; DI unsigned xb_ld(unsigned* p)              { return __hip_atomic_load(p, __ATOMIC_RELAXED, __HIP_MEMORY_SCOPE_AGENT); }
; #define XB_SPIN(cond, bar) do { unsigned _sp = 0; while (cond) { __builtin_amdgcn_s_sleep(1); \
;     if ((++_sp & 255u) == 0u) { if (xb_ld(&(bar)[XB_TMO])) break; if (_sp > XB_SPIN_CAP) { atomicAdd(&(bar)[XB_TMO], 1u); break; } } } } while (0)
; DI void xcd_barrier(unsigned* bar, volatile __attribute__((address_space(3))) unsigned* st) {
;     ...
;             XB_SPIN(xb_ld(&bar[XB_XGEN(x)]) == gen, bar);
;             __builtin_amdgcn_fence(__ATOMIC_ACQUIRE, "agent");
;             asm volatile("s_waitcnt vmcnt(0)" ::: "memory");
.LBB0_163:
	s_or_b64 exec, exec, s[8:9]
	s_waitcnt vmcnt(0)
	s_waitcnt vmcnt(0)

; DI unsigned xb_ld(unsigned* p)              { return __hip_atomic_load(p, __ATOMIC_RELAXED, __HIP_MEMORY_SCOPE_AGENT); }
; DI unsigned xb_add(unsigned* p, unsigned v) { return __hip_atomic_fetch_add(p, v, __ATOMIC_RELAXED, __HIP_MEMORY_SCOPE_AGENT); }
; #define XB_SPIN(cond, bar) do { unsigned _sp = 0; while (cond) { __builtin_amdgcn_s_sleep(1); \
;     if ((++_sp & 255u) == 0u) { if (xb_ld(&(bar)[XB_TMO])) break; if (_sp > XB_SPIN_CAP) { atomicAdd(&(bar)[XB_TMO], 1u); break; } } } } while (0)
; DI void xcd_barrier(unsigned* bar, volatile __attribute__((address_space(3))) unsigned* st) {
;     ...
;         const unsigned old = xb_add(&bar[XB_XSUB(x)], 1u);
;         const unsigned gen = old / nloc;
;         if (old + 1u == (gen + 1u) * nloc) {
;             __builtin_amdgcn_fence(__ATOMIC_RELEASE, "agent");
;             asm volatile("s_waitcnt vmcnt(0)" ::: "memory");
;             const unsigned og = xb_add(&bar[XB_TOP], 1u);
;             const unsigned tg = og / nx;
;             if (og + 1u == (tg + 1u) * nx) xb_add(&bar[XB_TOPGEN], 1u);
;             else XB_SPIN(xb_ld(&bar[XB_TOPGEN]) == tg, bar);
;             __builtin_amdgcn_fence(__ATOMIC_ACQUIRE, "agent");
;             xb_add(&bar[XB_XGEN(x)], 1u);
;             asm volatile("s_waitcnt vmcnt(0)" ::: "memory");
;         } else {
;             XB_SPIN(xb_ld(&bar[XB_XGEN(x)]) == gen, bar);
;             __builtin_amdgcn_fence(__ATOMIC_ACQUIRE, "agent");
.LBB0_240:
	s_or_b64 exec, exec, s[10:11]
	v_cvt_f32_u32_e32 v4, v2
	s_waitcnt vmcnt(0)
	v_readfirstlane_b32 s3, v3
	v_sub_u32_e32 v3, 0, v2
	v_rcp_iflag_f32_e32 v4, v4
	v_add_u32_e32 v5, s3, v0
	v_mul_f32_e32 v4, 0x4f7ffffe, v4
	v_cvt_u32_f32_e32 v4, v4
	v_mul_lo_u32 v0, v3, v4
	v_mul_hi_u32 v0, v4, v0
	v_add_u32_e32 v0, v4, v0
	v_mul_hi_u32 v0, v5, v0
	v_mul_lo_u32 v3, v0, v2
	v_sub_u32_e32 v3, v5, v3
	v_add_u32_e32 v4, 1, v0
	v_cmp_ge_u32_e32 vcc, v3, v2
	s_nop 1
	v_cndmask_b32_e32 v0, v0, v4, vcc
	v_sub_u32_e32 v4, v3, v2
	v_cndmask_b32_e32 v3, v3, v4, vcc
	v_add_u32_e32 v4, 1, v0
	v_cmp_ge_u32_e32 vcc, v3, v2
	v_add_u32_e32 v3, 1, v5
	s_nop 0
	v_cndmask_b32_e32 v0, v0, v4, vcc
	v_mul_lo_u32 v4, v2, v0
	v_add_u32_e32 v2, v4, v2
	v_cmp_ne_u32_e32 vcc, v3, v2
	s_and_saveexec_b64 s[8:9], vcc
	s_xor_b64 s[8:9], exec, s[8:9]
	s_cbranch_execz .LBB0_254
	buffer_inv sc1
	s_waitcnt lgkmcnt(0)
	v_mov_b32_e32 v1, 0x2000
	global_load_dword v1, v1, s[6:7] offset:1024 sc1
	s_add_u32 s14, s6, 0x2400
	s_addc_u32 s15, s7, 0
	s_waitcnt vmcnt(0)
	v_cmp_eq_u32_e32 vcc, v1, v0
	s_and_saveexec_b64 s[10:11], vcc
	s_cbranch_execz .LBB0_253
	s_add_u32 s12, s70, 0x34e2300
	s_addc_u32 s13, s71, 0
	s_mov_b32 s3, 1
	s_mov_b64 s[16:17], 0
	v_mov_b32_e32 v1, 0
	s_branch .LBB0_244

; DI unsigned xb_ld(unsigned* p)              { return __hip_atomic_load(p, __ATOMIC_RELAXED, __HIP_MEMORY_SCOPE_AGENT); }
; #define XB_SPIN(cond, bar) do { unsigned _sp = 0; while (cond) { __builtin_amdgcn_s_sleep(1); \
;     if ((++_sp & 255u) == 0u) { if (xb_ld(&(bar)[XB_TMO])) break; if (_sp > XB_SPIN_CAP) { atomicAdd(&(bar)[XB_TMO], 1u); break; } } } } while (0)
; DI void xcd_barrier(unsigned* bar, volatile __attribute__((address_space(3))) unsigned* st) {
;     ...
;             XB_SPIN(xb_ld(&bar[XB_XGEN(x)]) == gen, bar);
;             __builtin_amdgcn_fence(__ATOMIC_ACQUIRE, "agent");
;             asm volatile("s_waitcnt vmcnt(0)" ::: "memory");
.LBB0_253:
	s_or_b64 exec, exec, s[10:11]
	s_waitcnt vmcnt(0)
	s_waitcnt vmcnt(0)

; DI unsigned xb_ld(unsigned* p)              { return __hip_atomic_load(p, __ATOMIC_RELAXED, __HIP_MEMORY_SCOPE_AGENT); }
; DI unsigned xb_add(unsigned* p, unsigned v) { return __hip_atomic_fetch_add(p, v, __ATOMIC_RELAXED, __HIP_MEMORY_SCOPE_AGENT); }
; #define XB_SPIN(cond, bar) do { unsigned _sp = 0; while (cond) { __builtin_amdgcn_s_sleep(1); \
;     if ((++_sp & 255u) == 0u) { if (xb_ld(&(bar)[XB_TMO])) break; if (_sp > XB_SPIN_CAP) { atomicAdd(&(bar)[XB_TMO], 1u); break; } } } } while (0)
; DI void xcd_barrier(unsigned* bar, volatile __attribute__((address_space(3))) unsigned* st) {
;     ...
;         const unsigned old = xb_add(&bar[XB_XSUB(x)], 1u);
;         const unsigned gen = old / nloc;
;         if (old + 1u == (gen + 1u) * nloc) {
;             __builtin_amdgcn_fence(__ATOMIC_RELEASE, "agent");
;             asm volatile("s_waitcnt vmcnt(0)" ::: "memory");
;             const unsigned og = xb_add(&bar[XB_TOP], 1u);
;             const unsigned tg = og / nx;
;             if (og + 1u == (tg + 1u) * nx) xb_add(&bar[XB_TOPGEN], 1u);
;             else XB_SPIN(xb_ld(&bar[XB_TOPGEN]) == tg, bar);
;             __builtin_amdgcn_fence(__ATOMIC_ACQUIRE, "agent");
;             xb_add(&bar[XB_XGEN(x)], 1u);
;             asm volatile("s_waitcnt vmcnt(0)" ::: "memory");
;         } else {
;             XB_SPIN(xb_ld(&bar[XB_XGEN(x)]) == gen, bar);
;             __builtin_amdgcn_fence(__ATOMIC_ACQUIRE, "agent");
.LBB0_400:
	s_or_b64 exec, exec, s[8:9]
	v_cvt_f32_u32_e32 v4, v2
	s_waitcnt vmcnt(0)
	v_readfirstlane_b32 s3, v3
	v_sub_u32_e32 v3, 0, v2
	v_rcp_iflag_f32_e32 v4, v4
	v_add_u32_e32 v5, s3, v0
	v_mul_f32_e32 v4, 0x4f7ffffe, v4
	v_cvt_u32_f32_e32 v4, v4
	v_mul_lo_u32 v0, v3, v4
	v_mul_hi_u32 v0, v4, v0
	v_add_u32_e32 v0, v4, v0
	v_mul_hi_u32 v0, v5, v0
	v_mul_lo_u32 v3, v0, v2
	v_sub_u32_e32 v3, v5, v3
	v_add_u32_e32 v4, 1, v0
	v_cmp_ge_u32_e32 vcc, v3, v2
	s_nop 1
	v_cndmask_b32_e32 v0, v0, v4, vcc
	v_sub_u32_e32 v4, v3, v2
	v_cndmask_b32_e32 v3, v3, v4, vcc
	v_add_u32_e32 v4, 1, v0
	v_cmp_ge_u32_e32 vcc, v3, v2
	v_add_u32_e32 v3, 1, v5
	s_nop 0
	v_cndmask_b32_e32 v0, v0, v4, vcc
	v_mul_lo_u32 v4, v2, v0
	v_add_u32_e32 v2, v4, v2
	v_cmp_ne_u32_e32 vcc, v3, v2
	s_and_saveexec_b64 s[6:7], vcc
	s_xor_b64 s[6:7], exec, s[6:7]
	s_cbranch_execz .LBB0_414
	buffer_inv sc1
	s_waitcnt lgkmcnt(0)
	v_mov_b32_e32 v1, 0x2000
	global_load_dword v1, v1, s[4:5] offset:1024 sc1
	s_add_u32 s12, s4, 0x2400
	s_addc_u32 s13, s5, 0
	s_waitcnt vmcnt(0)
	v_cmp_eq_u32_e32 vcc, v1, v0
	s_and_saveexec_b64 s[8:9], vcc
	s_cbranch_execz .LBB0_413
	s_add_u32 s10, s70, 0x34e2300
	s_addc_u32 s11, s71, 0
	s_mov_b32 s3, 1
	s_mov_b64 s[16:17], 0
	v_mov_b32_e32 v1, 0
	s_branch .LBB0_404

; DI unsigned xb_ld(unsigned* p)              { return __hip_atomic_load(p, __ATOMIC_RELAXED, __HIP_MEMORY_SCOPE_AGENT); }
; DI unsigned xb_add(unsigned* p, unsigned v) { return __hip_atomic_fetch_add(p, v, __ATOMIC_RELAXED, __HIP_MEMORY_SCOPE_AGENT); }
; #define XB_SPIN(cond, bar) do { unsigned _sp = 0; while (cond) { __builtin_amdgcn_s_sleep(1); \
;     if ((++_sp & 255u) == 0u) { if (xb_ld(&(bar)[XB_TMO])) break; if (_sp > XB_SPIN_CAP) { atomicAdd(&(bar)[XB_TMO], 1u); break; } } } } while (0)
; DI void xcd_barrier(unsigned* bar, volatile __attribute__((address_space(3))) unsigned* st) {
;     ...
;         const unsigned old = xb_add(&bar[XB_XSUB(x)], 1u);
;         const unsigned gen = old / nloc;
;         if (old + 1u == (gen + 1u) * nloc) {
;             __builtin_amdgcn_fence(__ATOMIC_RELEASE, "agent");
;             asm volatile("s_waitcnt vmcnt(0)" ::: "memory");
;             const unsigned og = xb_add(&bar[XB_TOP], 1u);
;             const unsigned tg = og / nx;
;             if (og + 1u == (tg + 1u) * nx) xb_add(&bar[XB_TOPGEN], 1u);
;             else XB_SPIN(xb_ld(&bar[XB_TOPGEN]) == tg, bar);
;             __builtin_amdgcn_fence(__ATOMIC_ACQUIRE, "agent");
;             xb_add(&bar[XB_XGEN(x)], 1u);
;             asm volatile("s_waitcnt vmcnt(0)" ::: "memory");
;         } else {
;             XB_SPIN(xb_ld(&bar[XB_XGEN(x)]) == gen, bar);
;             __builtin_amdgcn_fence(__ATOMIC_ACQUIRE, "agent");
.LBB0_490:
	s_or_b64 exec, exec, s[10:11]
	v_cvt_f32_u32_e32 v4, v2
	s_waitcnt vmcnt(0)
	v_readfirstlane_b32 s3, v3
	v_sub_u32_e32 v3, 0, v2
	v_rcp_iflag_f32_e32 v4, v4
	v_add_u32_e32 v5, s3, v0
	v_mul_f32_e32 v4, 0x4f7ffffe, v4
	v_cvt_u32_f32_e32 v4, v4
	v_mul_lo_u32 v0, v3, v4
	v_mul_hi_u32 v0, v4, v0
	v_add_u32_e32 v0, v4, v0
	v_mul_hi_u32 v0, v5, v0
	v_mul_lo_u32 v3, v0, v2
	v_sub_u32_e32 v3, v5, v3
	v_add_u32_e32 v4, 1, v0
	v_cmp_ge_u32_e32 vcc, v3, v2
	s_nop 1
	v_cndmask_b32_e32 v0, v0, v4, vcc
	v_sub_u32_e32 v4, v3, v2
	v_cndmask_b32_e32 v3, v3, v4, vcc
	v_add_u32_e32 v4, 1, v0
	v_cmp_ge_u32_e32 vcc, v3, v2
	v_add_u32_e32 v3, 1, v5
	s_nop 0
	v_cndmask_b32_e32 v0, v0, v4, vcc
	v_mul_lo_u32 v4, v2, v0
	v_add_u32_e32 v2, v4, v2
	v_cmp_ne_u32_e32 vcc, v3, v2
	s_and_saveexec_b64 s[8:9], vcc
	s_xor_b64 s[8:9], exec, s[8:9]
	s_cbranch_execz .LBB0_504
	buffer_inv sc1
	s_waitcnt lgkmcnt(0)
	v_mov_b32_e32 v1, 0x2000
	global_load_dword v1, v1, s[4:5] offset:1024 sc1
	s_add_u32 s14, s4, 0x2400
	s_addc_u32 s15, s5, 0
	s_waitcnt vmcnt(0)
	v_cmp_eq_u32_e32 vcc, v1, v0
	s_and_saveexec_b64 s[10:11], vcc
	s_cbranch_execz .LBB0_503
	s_add_u32 s12, s70, 0x34e2300
	s_addc_u32 s13, s71, 0
	s_mov_b32 s3, 1
	s_mov_b64 s[16:17], 0
	v_mov_b32_e32 v1, 0
	s_branch .LBB0_494

; DI unsigned xb_ld(unsigned* p)              { return __hip_atomic_load(p, __ATOMIC_RELAXED, __HIP_MEMORY_SCOPE_AGENT); }
; DI unsigned xb_add(unsigned* p, unsigned v) { return __hip_atomic_fetch_add(p, v, __ATOMIC_RELAXED, __HIP_MEMORY_SCOPE_AGENT); }
; #define XB_SPIN(cond, bar) do { unsigned _sp = 0; while (cond) { __builtin_amdgcn_s_sleep(1); \
;     if ((++_sp & 255u) == 0u) { if (xb_ld(&(bar)[XB_TMO])) break; if (_sp > XB_SPIN_CAP) { atomicAdd(&(bar)[XB_TMO], 1u); break; } } } } while (0)
; DI void xcd_barrier(unsigned* bar, volatile __attribute__((address_space(3))) unsigned* st) {
;     ...
;         const unsigned old = xb_add(&bar[XB_XSUB(x)], 1u);
;         const unsigned gen = old / nloc;
;         if (old + 1u == (gen + 1u) * nloc) {
;             __builtin_amdgcn_fence(__ATOMIC_RELEASE, "agent");
;             asm volatile("s_waitcnt vmcnt(0)" ::: "memory");
;             const unsigned og = xb_add(&bar[XB_TOP], 1u);
;             const unsigned tg = og / nx;
;             if (og + 1u == (tg + 1u) * nx) xb_add(&bar[XB_TOPGEN], 1u);
;             else XB_SPIN(xb_ld(&bar[XB_TOPGEN]) == tg, bar);
;             __builtin_amdgcn_fence(__ATOMIC_ACQUIRE, "agent");
;             xb_add(&bar[XB_XGEN(x)], 1u);
;             asm volatile("s_waitcnt vmcnt(0)" ::: "memory");
;         } else {
;             XB_SPIN(xb_ld(&bar[XB_XGEN(x)]) == gen, bar);
.LBB0_1016:
	s_or_b64 exec, exec, s[12:13]
	v_cvt_f32_u32_e32 v4, v2
	s_waitcnt vmcnt(0)
	v_readfirstlane_b32 s3, v3
	v_sub_u32_e32 v3, 0, v2
	v_rcp_iflag_f32_e32 v4, v4
	v_add_u32_e32 v5, s3, v0
	v_mul_f32_e32 v4, 0x4f7ffffe, v4
	v_cvt_u32_f32_e32 v4, v4
	v_mul_lo_u32 v0, v3, v4
	v_mul_hi_u32 v0, v4, v0
	v_add_u32_e32 v0, v4, v0
	v_mul_hi_u32 v0, v5, v0
	v_mul_lo_u32 v3, v0, v2
	v_sub_u32_e32 v3, v5, v3
	v_add_u32_e32 v4, 1, v0
	v_cmp_ge_u32_e32 vcc, v3, v2
	s_nop 1
	v_cndmask_b32_e32 v0, v0, v4, vcc
	v_sub_u32_e32 v4, v3, v2
	v_cndmask_b32_e32 v3, v3, v4, vcc
	v_add_u32_e32 v4, 1, v0
	v_cmp_ge_u32_e32 vcc, v3, v2
	v_add_u32_e32 v3, 1, v5
	s_nop 0
	v_cndmask_b32_e32 v0, v0, v4, vcc
	v_mul_lo_u32 v4, v2, v0
	v_add_u32_e32 v2, v4, v2
	v_cmp_ne_u32_e32 vcc, v3, v2
	s_and_saveexec_b64 s[8:9], vcc
	s_xor_b64 s[8:9], exec, s[8:9]
	s_cbranch_execz .LBB0_1030
	buffer_inv sc1
	s_waitcnt lgkmcnt(0)
	v_mov_b32_e32 v1, 0x2000
	global_load_dword v1, v1, s[6:7] offset:1024 sc1
	s_add_u32 s16, s6, 0x2400
	s_addc_u32 s17, s7, 0
	s_waitcnt vmcnt(0)
	v_cmp_eq_u32_e32 vcc, v1, v0
	s_and_saveexec_b64 s[12:13], vcc
	s_cbranch_execz .LBB0_1029
	s_add_u32 s14, s70, 0x34e2300
	s_addc_u32 s15, s71, 0
	s_mov_b32 s3, 1
	s_mov_b64 s[18:19], 0
	v_mov_b32_e32 v1, 0
	s_branch .LBB0_1020

; DI unsigned xb_ld(unsigned* p)              { return __hip_atomic_load(p, __ATOMIC_RELAXED, __HIP_MEMORY_SCOPE_AGENT); }
; #define XB_SPIN(cond, bar) do { unsigned _sp = 0; while (cond) { __builtin_amdgcn_s_sleep(1); \
;     if ((++_sp & 255u) == 0u) { if (xb_ld(&(bar)[XB_TMO])) break; if (_sp > XB_SPIN_CAP) { atomicAdd(&(bar)[XB_TMO], 1u); break; } } } } while (0)
; DI void xcd_barrier(unsigned* bar, volatile __attribute__((address_space(3))) unsigned* st) {
;     ...
;             XB_SPIN(xb_ld(&bar[XB_XGEN(x)]) == gen, bar);
;             __builtin_amdgcn_fence(__ATOMIC_ACQUIRE, "agent");
;             asm volatile("s_waitcnt vmcnt(0)" ::: "memory");
.LBB0_1029:
	s_or_b64 exec, exec, s[12:13]
	s_waitcnt vmcnt(0)
	s_waitcnt vmcnt(0)

; DI unsigned xb_ld(unsigned* p)              { return __hip_atomic_load(p, __ATOMIC_RELAXED, __HIP_MEMORY_SCOPE_AGENT); }
; DI unsigned xb_add(unsigned* p, unsigned v) { return __hip_atomic_fetch_add(p, v, __ATOMIC_RELAXED, __HIP_MEMORY_SCOPE_AGENT); }
; #define XB_SPIN(cond, bar) do { unsigned _sp = 0; while (cond) { __builtin_amdgcn_s_sleep(1); \
;     if ((++_sp & 255u) == 0u) { if (xb_ld(&(bar)[XB_TMO])) break; if (_sp > XB_SPIN_CAP) { atomicAdd(&(bar)[XB_TMO], 1u); break; } } } } while (0)
; DI void xcd_barrier(unsigned* bar, volatile __attribute__((address_space(3))) unsigned* st) {
;     ...
;         const unsigned old = xb_add(&bar[XB_XSUB(x)], 1u);
;         const unsigned gen = old / nloc;
;         if (old + 1u == (gen + 1u) * nloc) {
;             __builtin_amdgcn_fence(__ATOMIC_RELEASE, "agent");
;             asm volatile("s_waitcnt vmcnt(0)" ::: "memory");
;             const unsigned og = xb_add(&bar[XB_TOP], 1u);
;             const unsigned tg = og / nx;
;             if (og + 1u == (tg + 1u) * nx) xb_add(&bar[XB_TOPGEN], 1u);
;             else XB_SPIN(xb_ld(&bar[XB_TOPGEN]) == tg, bar);
;             __builtin_amdgcn_fence(__ATOMIC_ACQUIRE, "agent");
;             xb_add(&bar[XB_XGEN(x)], 1u);
;             asm volatile("s_waitcnt vmcnt(0)" ::: "memory");
;         } else {
;             XB_SPIN(xb_ld(&bar[XB_XGEN(x)]) == gen, bar);
.LBB0_1110:
	s_or_b64 exec, exec, s[16:17]
	v_cvt_f32_u32_e32 v4, v2
	s_waitcnt vmcnt(0)
	v_readfirstlane_b32 s3, v3
	v_sub_u32_e32 v3, 0, v2
	v_rcp_iflag_f32_e32 v4, v4
	v_add_u32_e32 v5, s3, v0
	v_mul_f32_e32 v4, 0x4f7ffffe, v4
	v_cvt_u32_f32_e32 v4, v4
	v_mul_lo_u32 v0, v3, v4
	v_mul_hi_u32 v0, v4, v0
	v_add_u32_e32 v0, v4, v0
	v_mul_hi_u32 v0, v5, v0
	v_mul_lo_u32 v3, v0, v2
	v_sub_u32_e32 v3, v5, v3
	v_add_u32_e32 v4, 1, v0
	v_cmp_ge_u32_e32 vcc, v3, v2
	s_nop 1
	v_cndmask_b32_e32 v0, v0, v4, vcc
	v_sub_u32_e32 v4, v3, v2
	v_cndmask_b32_e32 v3, v3, v4, vcc
	v_add_u32_e32 v4, 1, v0
	v_cmp_ge_u32_e32 vcc, v3, v2
	v_add_u32_e32 v3, 1, v5
	s_nop 0
	v_cndmask_b32_e32 v0, v0, v4, vcc
	v_mul_lo_u32 v4, v2, v0
	v_add_u32_e32 v2, v4, v2
	v_cmp_ne_u32_e32 vcc, v3, v2
	s_and_saveexec_b64 s[8:9], vcc
	s_xor_b64 s[8:9], exec, s[8:9]
	s_cbranch_execz .LBB0_1124
	buffer_inv sc1
	s_waitcnt lgkmcnt(0)
	v_mov_b32_e32 v1, 0x2000
	global_load_dword v1, v1, s[6:7] offset:1024 sc1
	s_add_u32 s20, s6, 0x2400
	s_addc_u32 s21, s7, 0
	s_waitcnt vmcnt(0)
	v_cmp_eq_u32_e32 vcc, v1, v0
	s_and_saveexec_b64 s[16:17], vcc
	s_cbranch_execz .LBB0_1123
	s_add_u32 s18, s70, 0x34e2300
	s_addc_u32 s19, s71, 0
	s_mov_b32 s3, 1
	s_mov_b64 s[22:23], 0
	v_mov_b32_e32 v1, 0
	s_branch .LBB0_1114

; DI unsigned xb_ld(unsigned* p)              { return __hip_atomic_load(p, __ATOMIC_RELAXED, __HIP_MEMORY_SCOPE_AGENT); }
; #define XB_SPIN(cond, bar) do { unsigned _sp = 0; while (cond) { __builtin_amdgcn_s_sleep(1); \
;     if ((++_sp & 255u) == 0u) { if (xb_ld(&(bar)[XB_TMO])) break; if (_sp > XB_SPIN_CAP) { atomicAdd(&(bar)[XB_TMO], 1u); break; } } } } while (0)
; DI void xcd_barrier(unsigned* bar, volatile __attribute__((address_space(3))) unsigned* st) {
;     ...
;             XB_SPIN(xb_ld(&bar[XB_XGEN(x)]) == gen, bar);
;             __builtin_amdgcn_fence(__ATOMIC_ACQUIRE, "agent");
;             asm volatile("s_waitcnt vmcnt(0)" ::: "memory");
.LBB0_1123:
	s_or_b64 exec, exec, s[16:17]
	s_waitcnt vmcnt(0)
	s_waitcnt vmcnt(0)

; DI unsigned xb_ld(unsigned* p)              { return __hip_atomic_load(p, __ATOMIC_RELAXED, __HIP_MEMORY_SCOPE_AGENT); }
; DI unsigned xb_add(unsigned* p, unsigned v) { return __hip_atomic_fetch_add(p, v, __ATOMIC_RELAXED, __HIP_MEMORY_SCOPE_AGENT); }
; #define XB_SPIN(cond, bar) do { unsigned _sp = 0; while (cond) { __builtin_amdgcn_s_sleep(1); \
;     if ((++_sp & 255u) == 0u) { if (xb_ld(&(bar)[XB_TMO])) break; if (_sp > XB_SPIN_CAP) { atomicAdd(&(bar)[XB_TMO], 1u); break; } } } } while (0)
; DI void xcd_barrier(unsigned* bar, volatile __attribute__((address_space(3))) unsigned* st) {
;     ...
;         const unsigned old = xb_add(&bar[XB_XSUB(x)], 1u);
;         const unsigned gen = old / nloc;
;         if (old + 1u == (gen + 1u) * nloc) {
;             __builtin_amdgcn_fence(__ATOMIC_RELEASE, "agent");
;             asm volatile("s_waitcnt vmcnt(0)" ::: "memory");
;             const unsigned og = xb_add(&bar[XB_TOP], 1u);
;             const unsigned tg = og / nx;
;             if (og + 1u == (tg + 1u) * nx) xb_add(&bar[XB_TOPGEN], 1u);
;             else XB_SPIN(xb_ld(&bar[XB_TOPGEN]) == tg, bar);
;             __builtin_amdgcn_fence(__ATOMIC_ACQUIRE, "agent");
;             xb_add(&bar[XB_XGEN(x)], 1u);
;             asm volatile("s_waitcnt vmcnt(0)" ::: "memory");
;         } else {
;             XB_SPIN(xb_ld(&bar[XB_XGEN(x)]) == gen, bar);
.LBB0_1249:
	s_or_b64 exec, exec, s[6:7]
	v_cvt_f32_u32_e32 v4, v2
	s_waitcnt vmcnt(0)
	v_readfirstlane_b32 s4, v3
	v_sub_u32_e32 v3, 0, v2
	v_rcp_iflag_f32_e32 v4, v4
	v_add_u32_e32 v5, s4, v0
	v_mul_f32_e32 v4, 0x4f7ffffe, v4
	v_cvt_u32_f32_e32 v4, v4
	v_mul_lo_u32 v0, v3, v4
	v_mul_hi_u32 v0, v4, v0
	v_add_u32_e32 v0, v4, v0
	v_mul_hi_u32 v0, v5, v0
	v_mul_lo_u32 v3, v0, v2
	v_sub_u32_e32 v3, v5, v3
	v_add_u32_e32 v4, 1, v0
	v_cmp_ge_u32_e32 vcc, v3, v2
	s_nop 1
	v_cndmask_b32_e32 v0, v0, v4, vcc
	v_sub_u32_e32 v4, v3, v2
	v_cndmask_b32_e32 v3, v3, v4, vcc
	v_add_u32_e32 v4, 1, v0
	v_cmp_ge_u32_e32 vcc, v3, v2
	v_add_u32_e32 v3, 1, v5
	s_nop 0
	v_cndmask_b32_e32 v0, v0, v4, vcc
	v_mul_lo_u32 v4, v2, v0
	v_add_u32_e32 v2, v4, v2
	v_cmp_ne_u32_e32 vcc, v3, v2
	s_and_saveexec_b64 s[4:5], vcc
	s_xor_b64 s[4:5], exec, s[4:5]
	s_cbranch_execz .LBB0_1263
	buffer_inv sc1
	s_waitcnt lgkmcnt(0)
	v_mov_b32_e32 v1, 0x2000
	global_load_dword v1, v1, s[2:3] offset:1024 sc1
	s_add_u32 s10, s2, 0x2400
	s_addc_u32 s11, s3, 0
	s_waitcnt vmcnt(0)
	v_cmp_eq_u32_e32 vcc, v1, v0
	s_and_saveexec_b64 s[6:7], vcc
	s_cbranch_execz .LBB0_1262
	s_add_u32 s8, s70, 0x34e2300
	s_addc_u32 s9, s71, 0
	s_mov_b32 s22, 1
	s_mov_b64 s[12:13], 0
	v_mov_b32_e32 v1, 0
	s_branch .LBB0_1253

; DI unsigned xb_ld(unsigned* p)              { return __hip_atomic_load(p, __ATOMIC_RELAXED, __HIP_MEMORY_SCOPE_AGENT); }
; #define XB_SPIN(cond, bar) do { unsigned _sp = 0; while (cond) { __builtin_amdgcn_s_sleep(1); \
;     if ((++_sp & 255u) == 0u) { if (xb_ld(&(bar)[XB_TMO])) break; if (_sp > XB_SPIN_CAP) { atomicAdd(&(bar)[XB_TMO], 1u); break; } } } } while (0)
; DI void xcd_barrier(unsigned* bar, volatile __attribute__((address_space(3))) unsigned* st) {
;     ...
;             XB_SPIN(xb_ld(&bar[XB_XGEN(x)]) == gen, bar);
;             __builtin_amdgcn_fence(__ATOMIC_ACQUIRE, "agent");
;             asm volatile("s_waitcnt vmcnt(0)" ::: "memory");
.LBB0_1262:
	s_or_b64 exec, exec, s[6:7]
	s_waitcnt vmcnt(0)
	s_waitcnt vmcnt(0)
